# in-proj GEMM start staggered by XCC id (1us per XCD)
# baseline (speedup 1.0000x reference)
; #define PG8_STAGE(bufoff, gbase, voff) do { _Pragma("unroll") for (int _i = 0; _i < 2; ++_i) \
;         __builtin_amdgcn_global_load_lds((const unsigned*)((const char*)(gbase) + (voff)[_i]), (PG8_LAS unsigned*)(lds + (bufoff) + ldsw + _i * 8192), 16, 0, 0); } while (0)
; #define PG8_WAIT_V(n) asm volatile("s_waitcnt vmcnt(" #n ")" ::: "memory")
; #define PG8_BAR __builtin_amdgcn_s_barrier()
; template <class Epi, class Sched, bool ALIGN_EPI = false, bool SP2 = false>
; __device__ __forceinline__ void gemm_phase(PG8_LAS unsigned char* lds, const Gemm g, const Sched& S, const Epi& E) {
;     int tid_ = threadIdx.x; asm volatile("" : "+v"(tid_));
;     const int tid = tid_, wid = __builtin_amdgcn_readfirstlane(tid >> 6), lane = tid & 63, wr = wid >> 2, wc = wid & 3, fr = lane & 15, fq = lane >> 4;
;     const int K = g.K, nt = K / BK;
;     unsigned voffA[2], voffB[2];
; #pragma unroll
;     for (int i = 0; i < 2; ++i) { int R, C; stage_rc(tid * 16 + i * 8192, R, C); const int Rb = Epi::PERM ? ((R & ~31) + perm32(R & 31)) : R;
;         voffA[i] = (unsigned)(R * K + C) * 2u; voffB[i] = (unsigned)(Rb * K + C) * 2u; }
;     const size_t kstep = (size_t)(BK * 2);
;     const size_t hstep = (size_t)HALF * K * 2;
;     const size_t tstep = 2 * hstep;
;     const unsigned ldsw = (unsigned)wid * 1024u;
;     const int aoff = lds_byte(wr * 64 + fr, fq * 8), boff = lds_byte(wc * 32 + fr, fq * 8);
;     ...
;     Unit cur, nxt; int ui = 0;
;     if (!S.next(0, cur)) return;
;     f32x4 acc[2][2][4][2];
; #pragma unroll
;     for (int a = 0; a < 2; ++a)
; #pragma unroll
;         for (int b = 0; b < 2; ++b)
; #pragma unroll
;             for (int m = 0; m < 4; ++m)
; #pragma unroll
;                 for (int n = 0; n < 2; ++n) acc[a][b][m][n] = (f32x4){0.f, 0.f, 0.f, 0.f};
;     bf16x8 At[4][2], B0[2][2], B1[2][2];
;     const char* cA = (const char*)g.A + (size_t)cur.pm * tstep; const char* cB = (const char*)g.Bt + (size_t)cur.pn * tstep;
;     S.a_ready(cur);
;     if constexpr (SP2) {
;         PG8_STAGE(PG8_SB(0, 0), cB, voffB); PG8_STAGE(PG8_SB(0, 1), cB + hstep, voffB); PG8_STAGE(PG8_SA(0, 0), cA, voffA); PG8_STAGE(PG8_SA(0, 1), cA + hstep, voffA);
;         if (wr == 1) PG8_BAR;
;         PG8_WAIT_V(2); PG8_BAR;
.LBB0_118:
	s_getreg_b32 s0, hwreg(HW_REG_XCC_ID, 0, 4)
	s_and_b32 s0, s0, 7
	s_mul_i32 s0, s0, 100
	s_memrealtime s[2:3]
	s_waitcnt lgkmcnt(0)
	s_mov_b32 s1, s2
.Lstag_g1:
	s_sleep 2
	s_memrealtime s[2:3]
	s_waitcnt lgkmcnt(0)
	s_sub_u32 s2, s2, s1
	s_cmp_lt_u32 s2, s0
	s_cbranch_scc1 .Lstag_g1
	s_mov_b64 s[0:1], s[66:67]
	v_mov_b32_e32 v0, v187
	v_readlane_b32 s2, v254, 7
	s_mov_b32 s40, s68
	v_mov_b32_e32 v0, v187
	v_readlane_b32 s3, v254, 8
	s_mul_i32 s50, s84, 0xc0
	s_and_b64 vcc, exec, s[2:3]
	v_readfirstlane_b32 s8, v0
	s_cbranch_vccz .LBB0_245
	v_lshlrev_b32_e32 v2, 4, v0
	v_add_u32_e32 v3, 0x2000, v2
	v_ashrrev_i32_e32 v4, 31, v3
	v_lshrrev_b32_e32 v4, 22, v4
	v_add_u32_e32 v4, v3, v4
	v_ashrrev_i32_e32 v10, 10, v4
	v_mul_i32_i24_e32 v4, 0x400, v10
	v_sub_u32_e32 v3, v3, v4
	v_lshrrev_b32_e32 v4, 4, v3
	v_bitop3_b32 v3, v4, v3, 32 bitop3:0x6c
	v_ashrrev_i32_e32 v4, 31, v3
	v_lshrrev_b32_e32 v4, 26, v4
	v_add_u32_e32 v4, v3, v4
	v_lshlrev_b32_e32 v5, 3, v10
	v_ashrrev_i32_e32 v11, 6, v4
	v_and_b32_e32 v5, -16, v5
	v_add_u32_e32 v5, v11, v5
	v_and_b32_e32 v6, 3, v11
	s_mov_b32 s2, 0xfffe0
	v_lshrrev_b32_e32 v7, 2, v5
	v_lshlrev_b32_e32 v8, 1, v5
	v_and_b32_e32 v4, 0xc0, v4
	v_and_or_b32 v6, v5, s2, v6
	v_and_b32_e32 v7, 4, v7
	v_and_b32_e32 v8, 24, v8
	v_sub_u32_e32 v3, v3, v4
	v_or3_b32 v6, v6, v7, v8
	v_lshlrev_b32_e32 v7, 5, v10
	v_ashrrev_i16_sdwa v3, v189, sext(v3) dst_sel:DWORD dst_unused:UNUSED_PAD src0_sel:DWORD src1_sel:BYTE_0
	v_and_b32_e32 v7, 32, v7
	v_bfe_i32 v12, v3, 0, 16
	v_add_lshl_u32 v3, v7, v12, 1
	v_lshl_add_u32 v166, v6, 12, v3
	v_lshl_add_u32 v168, v5, 12, v3
	v_bfe_i32 v3, v0, 27, 1
	v_lshrrev_b32_e32 v3, 22, v3
	v_add_u32_e32 v3, v2, v3
	s_load_dwordx2 s[18:19], s[0:1], 0x40
	s_load_dwordx4 s[20:23], s[0:1], 0x18
	v_and_b32_e32 v3, 0xfffffc00, v3
	v_sub_u32_e32 v2, v2, v3
	v_lshrrev_b32_e32 v3, 4, v2
	v_ashrrev_i32_e32 v4, 31, v0
	v_bitop3_b32 v2, v3, v2, 32 bitop3:0x6c
	v_lshrrev_b32_e32 v4, 26, v4
	v_ashrrev_i32_e32 v3, 31, v2
	v_add_u32_e32 v4, v0, v4
	s_waitcnt lgkmcnt(0)
	s_add_u32 s41, s18, 0xa100000
	v_lshrrev_b32_e32 v3, 26, v3
	v_ashrrev_i32_e32 v14, 6, v4
	s_addc_u32 s42, s19, 0
	s_lshl_b64 s[0:1], s[84:85], 25
	v_add_u32_e32 v3, v2, v3
	v_lshlrev_b32_e32 v4, 3, v14
	s_add_u32 s0, s18, s0
	v_ashrrev_i32_e32 v13, 6, v3
	v_and_b32_e32 v4, -16, v4
	s_addc_u32 s1, s19, s1
	v_add_u32_e32 v4, v13, v4
	s_add_u32 s43, s0, 0x100000
	v_and_b32_e32 v5, 3, v13
	v_lshrrev_b32_e32 v6, 2, v4
	v_lshlrev_b32_e32 v7, 1, v4
	v_and_b32_e32 v3, 0xc0, v3
	s_addc_u32 s44, s1, 0
	s_ashr_i32 s1, s8, 6
	v_and_or_b32 v5, v4, s2, v5
	v_and_b32_e32 v6, 4, v6
	v_and_b32_e32 v7, 24, v7
	v_sub_u32_e32 v2, v2, v3
	s_ashr_i32 s0, s8, 8
	s_lshl_b32 s45, s1, 10
	v_or3_b32 v5, v5, v6, v7
	v_lshlrev_b32_e32 v6, 5, v14
	v_ashrrev_i16_sdwa v2, v189, sext(v2) dst_sel:DWORD dst_unused:UNUSED_PAD src0_sel:DWORD src1_sel:BYTE_0
	v_readlane_b32 s2, v254, 24
	v_and_b32_e32 v6, 32, v6
	v_bfe_i32 v15, v2, 0, 16
	v_readlane_b32 s3, v254, 25
	s_add_u32 s4, s43, s2
	v_add_lshl_u32 v2, v6, v15, 1
	s_addc_u32 s5, s44, s3
	s_add_i32 s46, s45, 0
	v_lshl_add_u32 v170, v5, 12, v2
	s_add_i32 m0, s46, 0x10000
	v_lshl_add_u32 v172, v4, 12, v2
	global_load_lds_dwordx4 v170, s[4:5]
	s_add_i32 m0, s46, 0x12000
	s_add_u32 s2, s4, 0x80000
	global_load_lds_dwordx4 v166, s[4:5]
	s_addc_u32 s3, s5, 0
	s_add_i32 m0, s46, 0x14000
	v_mov_b32_e32 v171, v1
	global_load_lds_dwordx4 v170, s[2:3]
	s_add_i32 m0, s46, 0x16000
	v_mov_b32_e32 v167, v1
	global_load_lds_dwordx4 v166, s[2:3]
	v_readlane_b32 s2, v254, 22
	v_readlane_b32 s3, v254, 23
	s_add_u32 s2, s41, s2
	s_addc_u32 s3, s42, s3
	s_add_i32 s47, s46, 0x2000
	s_mov_b32 m0, s46
	s_add_u32 s10, s2, 0x80000
	global_load_lds_dwordx4 v172, s[2:3]
	s_mov_b32 m0, s47
	s_addc_u32 s11, s3, 0
	s_add_i32 s48, s46, 0x4000
	global_load_lds_dwordx4 v168, s[2:3]
	s_mov_b32 m0, s48
	s_add_i32 s49, s46, 0x6000
	global_load_lds_dwordx4 v172, s[10:11]
	s_mov_b32 m0, s49
	v_mov_b32_e32 v173, v1
	global_load_lds_dwordx4 v168, s[10:11]
	v_mov_b32_e32 v169, v1
	s_cmp_eq_u32 s0, 1
	v_lshl_add_u64 v[8:9], s[4:5], 0, v[170:171]
	v_lshl_add_u64 v[6:7], s[4:5], 0, v[166:167]
	v_lshl_add_u64 v[2:3], s[2:3], 0, v[172:173]
	s_cselect_b64 s[24:25], -1, 0
	s_cmp_lg_u32 s0, 1
	v_lshl_add_u64 v[4:5], s[2:3], 0, v[168:169]
	s_cbranch_scc1 .LBB0_121
	s_barrier
